# prompt attention: post-PV barrier and staging LDS writes moved ahead of the last four PV MFMAs of each half-step (write latency hidden; tight barrier-to-barrier window nearly empty)
# baseline (speedup 1.0000x reference)
; __device__ __forceinline__ void finishSM(f32x16& p0, f32x16& p1, float alpha, float& l_reg, bf16x8& pa0, bf16x8& pa1, bf16x8& pa2, bf16x8& pa3) {
;     for (int r = 0; r < 16; ++r) p1[r] = __builtin_amdgcn_exp2f(p1[r]);
;     float ps = 0; for (int r = 0; r < 16; ++r) ps += p0[r]; for (int r = 0; r < 16; ++r) ps += p1[r];
;     { auto rr = __builtin_amdgcn_permlane32_swap(__float_as_uint(ps), __float_as_uint(ps), false, false);
;       ps = __uint_as_float(rr[0]) + __uint_as_float(rr[1]); }
;     l_reg = l_reg * alpha + ps;
;     ...
;     PK4(p0, 0, pa0); PK4(p0, 8, pa1); PK4(p1, 0, pa2); PK4(p1, 8, pa3);
;     ...
; }
; template <int KB, bool SK>
; __device__ __forceinline__ void qkt(f32x16& p0, f32x16& p1, const char* K_lds, const float* B_lds, int r32, int hi, const bf16x8* qr, bool act) {
;     if (SK && !act) { const float NEG = -__builtin_inff();
; #pragma unroll
;         for (int r = 0; r < 16; ++r) { p0[r] = NEG; p1[r] = NEG; } return; }
;     ...
;     p0 = f32x16{}; p1 = f32x16{};
;     ...
;     p0 = *(const f32x16*)(B_lds + KB * 64 + hi * 32); p1 = *(const f32x16*)(B_lds + KB * 64 + hi * 32 + 16);
;     ...
;     const char* kb[4];
; #pragma unroll
;     for (int dd = 0; dd < 4; ++dd) kb[dd] = K_lds + KB * SHM_K + KSWZ(r32, (dd * 16 + hi * 8) * 2);
; #pragma unroll
;     for (int d0 = 0; d0 < 8; ++d0) { const char* a = kb[d0 & 3] + (d0 >> 2) * 128;
;         bf16x8 b0 = *reinterpret_cast<const bf16x8*>(a);
;         bf16x8 b1 = *reinterpret_cast<const bf16x8*>(a + 32 * 256);
;         p0 = __builtin_amdgcn_mfma_f32_32x32x16_bf16(b0, qr[d0], p0, 0, 0, 0);
;         p1 = __builtin_amdgcn_mfma_f32_32x32x16_bf16(b1, qr[d0], p1, 0, 0, 0); }
; }
.LBB0_1247:
	v_add_u32_e32 v200, v230, v219
	v_add_u32_e32 v248, s68, v200
	v_add_u32_e32 v200, 1, v248
	v_lshl_add_u64 v[2:3], v[200:201], 2, s[66:67]
	v_mov_b32_e32 v15, v1
	v_add_u32_e32 v200, 0x10000, v14
	v_lshlrev_b64 v[10:11], 1, v[14:15]
	v_lshlrev_b64 v[12:13], 1, v[200:201]
	global_load_dword v246, v[2:3], off
	v_lshl_add_u64 v[2:3], s[64:65], 0, v[10:11]
	v_lshl_add_u64 v[6:7], s[64:65], 0, v[12:13]
	v_lshl_add_u64 v[10:11], s[62:63], 0, v[10:11]
	global_load_dwordx4 v[2:5], v[2:3], off
	s_nop 0
	global_load_dwordx4 v[6:9], v[6:7], off
	v_lshl_add_u64 v[210:211], s[62:63], 0, v[12:13]
	global_load_dwordx4 v[10:13], v[10:11], off
	s_nop 0
	global_load_dwordx4 v[210:213], v[210:211], off
	v_add_u32_e32 v0, 0x10900, v236
	ds_read_b128 v[100:103], v0
	ds_read_b128 v[104:107], v0 offset:16
	ds_read_b128 v[108:111], v0 offset:32
	s_waitcnt vmcnt(7)
	ds_read_b128 v[112:115], v0 offset:48
	ds_read_b128 v[96:99], v0 offset:112
	ds_read_b128 v[92:95], v0 offset:96
	ds_read_b128 v[88:91], v0 offset:80
	ds_read_b128 v[84:87], v0 offset:64
	ds_read_b128 v[202:205], v235 offset:49152
	ds_read_b128 v[206:209], v235 offset:57344
	v_add_f32_e32 v80, 0, v191
	v_add_f32_e32 v80, v193, v80
	v_add_f32_e32 v80, v189, v80
	s_waitcnt lgkmcnt(1)
	v_mfma_f32_32x32x16_bf16 v[100:115], v[202:205], v[172:175], v[100:115]
	v_add_f32_e32 v80, v192, v80
	v_add_f32_e32 v80, v188, v80
	v_add_f32_e32 v80, v190, v80
	v_add_f32_e32 v80, v186, v80
	v_add_f32_e32 v80, v187, v80
	v_add_f32_e32 v80, v182, v80
	v_add_f32_e32 v80, v185, v80
	s_waitcnt lgkmcnt(0)
	v_mfma_f32_32x32x16_bf16 v[84:99], v[206:209], v[172:175], v[84:99]
	ds_read_b128 v[202:205], v234 offset:49152
	ds_read_b128 v[206:209], v234 offset:57344
	v_add_f32_e32 v80, v179, v80
	v_add_f32_e32 v80, v183, v80
	v_exp_f32_e32 v0, v142
	v_add_f32_e32 v80, v177, v80
	v_add_f32_e32 v80, v184, v80
	v_add_f32_e32 v80, v178, v80
	s_waitcnt lgkmcnt(1)
	v_mfma_f32_32x32x16_bf16 v[100:115], v[202:205], v[168:171], v[100:115]
	v_add_f32_e32 v80, v181, v80
	v_add_f32_e32 v80, v0, v80
	v_exp_f32_e32 v194, v135
	v_exp_f32_e32 v195, v132
	v_exp_f32_e32 v196, v133
	v_exp_f32_e32 v197, v130
	v_exp_f32_e32 v198, v131
	s_waitcnt lgkmcnt(0)
	v_mfma_f32_32x32x16_bf16 v[84:99], v[206:209], v[168:171], v[84:99]
	ds_read_b128 v[202:205], v233 offset:49152
	ds_read_b128 v[206:209], v233 offset:57344
	v_exp_f32_e32 v127, v128
	v_exp_f32_e32 v128, v129
	s_sub_i32 s4, s68, 63
	s_waitcnt lgkmcnt(1)
	v_mfma_f32_32x32x16_bf16 v[100:115], v[202:205], v[164:167], v[100:115]
	s_waitcnt lgkmcnt(0)
	v_mfma_f32_32x32x16_bf16 v[84:99], v[206:209], v[164:167], v[84:99]
	ds_read_b128 v[202:205], v232 offset:49152
	ds_read_b128 v[206:209], v232 offset:57344
	s_waitcnt lgkmcnt(1)
	v_mfma_f32_32x32x16_bf16 v[100:115], v[202:205], v[160:163], v[100:115]
	s_waitcnt lgkmcnt(0)
	v_mfma_f32_32x32x16_bf16 v[84:99], v[206:209], v[160:163], v[84:99]
	ds_read_b128 v[202:205], v235 offset:49280
	ds_read_b128 v[206:209], v235 offset:57472
	s_waitcnt lgkmcnt(1)
	v_mfma_f32_32x32x16_bf16 v[100:115], v[202:205], v[156:159], v[100:115]
	s_waitcnt lgkmcnt(0)
	v_mfma_f32_32x32x16_bf16 v[84:99], v[206:209], v[156:159], v[84:99]
	ds_read_b128 v[202:205], v234 offset:49280
	ds_read_b128 v[206:209], v234 offset:57472
	s_waitcnt lgkmcnt(1)
	v_mfma_f32_32x32x16_bf16 v[100:115], v[202:205], v[152:155], v[100:115]
	s_waitcnt lgkmcnt(0)
	v_mfma_f32_32x32x16_bf16 v[84:99], v[206:209], v[152:155], v[84:99]
	ds_read_b128 v[202:205], v233 offset:49280
	ds_read_b128 v[206:209], v233 offset:57472
	s_waitcnt lgkmcnt(1)
	v_mfma_f32_32x32x16_bf16 v[100:115], v[202:205], v[148:151], v[100:115]
	s_waitcnt lgkmcnt(0)
	v_mfma_f32_32x32x16_bf16 v[84:99], v[206:209], v[148:151], v[84:99]
	ds_read_b128 v[202:205], v232 offset:49280
	ds_read_b128 v[206:209], v232 offset:57472
	s_waitcnt lgkmcnt(1)
	v_mfma_f32_32x32x16_bf16 v[100:115], v[202:205], v[144:147], v[100:115]
	v_exp_f32_e32 v202, v143
	v_exp_f32_e32 v203, v140
	v_exp_f32_e32 v204, v141
	v_exp_f32_e32 v205, v138
	v_add_f32_e32 v80, v202, v80
	v_add_f32_e32 v80, v203, v80
	v_add_f32_e32 v80, v204, v80
	s_waitcnt lgkmcnt(0)
	v_mfma_f32_32x32x16_bf16 v[84:99], v[206:209], v[144:147], v[84:99]
	v_exp_f32_e32 v206, v139
	v_exp_f32_e32 v207, v136
	v_exp_f32_e32 v208, v137
	v_exp_f32_e32 v209, v134
	v_add_f32_e32 v80, v205, v80
	v_add_f32_e32 v80, v206, v80
	v_add_f32_e32 v80, v207, v80
	v_add_f32_e32 v80, v208, v80
	v_add_f32_e32 v80, v209, v80
	v_add_f32_e32 v80, v194, v80
	v_add_f32_e32 v80, v195, v80
	v_add_f32_e32 v80, v196, v80
	v_add_f32_e32 v80, v197, v80
	v_add_f32_e32 v80, v198, v80
	v_add_f32_e32 v80, v127, v80
	v_add_f32_e32 v244, v128, v80
	v_mov_b32_e32 v245, v244
	s_nop 1
	v_permlane32_swap_b32_e32 v244, v245
	v_cvt_pk_bf16_f32 v80, v191, v193
	v_cvt_pk_bf16_f32 v81, v189, v192
	v_cvt_pk_bf16_f32 v82, v188, v190
	v_cvt_pk_bf16_f32 v83, v186, v187
	s_waitcnt vmcnt(6)
	v_cvt_pk_bf16_f32 v116, v182, v185
	v_cvt_pk_bf16_f32 v117, v179, v183
	v_cvt_pk_bf16_f32 v118, v177, v184
	v_cvt_pk_bf16_f32 v119, v178, v181
	s_waitcnt vmcnt(5)
	v_cvt_pk_bf16_f32 v120, v0, v202
	v_cvt_pk_bf16_f32 v121, v203, v204
	v_cvt_pk_bf16_f32 v122, v205, v206
	v_cvt_pk_bf16_f32 v123, v207, v208
	v_cvt_pk_bf16_f32 v124, v209, v194
	v_cvt_pk_bf16_f32 v125, v195, v196
	v_cvt_pk_bf16_f32 v126, v197, v198
	v_cvt_pk_bf16_f32 v127, v127, v128
	v_permlane32_swap_b32_e32 v80, v82
	v_permlane32_swap_b32_e32 v81, v83
	v_permlane32_swap_b32_e32 v116, v118
	v_permlane32_swap_b32_e32 v117, v119
	v_permlane32_swap_b32_e32 v120, v122
	v_permlane32_swap_b32_e32 v121, v123
	v_permlane32_swap_b32_e32 v124, v126
	v_permlane32_swap_b32_e32 v125, v127
	ds_read_b64_tr_b16 v[128:129], v227 offset:0
	ds_read_b64_tr_b16 v[130:131], v227 offset:0x800
	ds_read_b64_tr_b16 v[132:133], v227 offset:0x1000
	ds_read_b64_tr_b16 v[134:135], v227 offset:0x1800
	ds_read_b64_tr_b16 v[136:137], v227 offset:0x2000
	ds_read_b64_tr_b16 v[138:139], v227 offset:0x2800
	ds_read_b64_tr_b16 v[140:141], v227 offset:0x3000
	ds_read_b64_tr_b16 v[142:143], v227 offset:0x3800
	s_waitcnt lgkmcnt(0)
; __device__ __forceinline__ void mask_tile(f32x16& p0, f32x16& p1, int dq, unsigned W) {
;     const float NEG = -__builtin_inff();
; #pragma unroll
;     for (int r = 0; r < 16; ++r) {
;         const int c = (r & 3) + 8 * (r >> 2);
;         if ((unsigned)(dq - c) >= W) p0[r] = NEG;
;         if ((unsigned)(dq - c - 32) >= W) p1[r] = NEG;
;     }
; }
; template <int VB, bool SK>
; __device__ __forceinline__ void pv_tile(f32x16* o, int vb0, bf16x8 pa0, bf16x8 pa1, bf16x8 pa2, bf16x8 pa3, bool act) {
;     ...
;     PV_D0(0); PV_D0(1); PV_D0(2); PV_D0(3);
	s_nop 0
	v_mfma_f32_32x32x16_bf16 v[64:79], v[80:83], v[128:131], v[64:79]
	ds_read_b64_tr_b16 v[128:129], v227 offset:0x200
	ds_read_b64_tr_b16 v[130:131], v227 offset:0xa00
	v_mfma_f32_32x32x16_bf16 v[64:79], v[116:119], v[132:135], v[64:79]
	ds_read_b64_tr_b16 v[132:133], v227 offset:0x1200
	ds_read_b64_tr_b16 v[134:135], v227 offset:0x1a00
	v_mfma_f32_32x32x16_bf16 v[64:79], v[120:123], v[136:139], v[64:79]
	ds_read_b64_tr_b16 v[136:137], v227 offset:0x2200
	ds_read_b64_tr_b16 v[138:139], v227 offset:0x2a00
	v_mfma_f32_32x32x16_bf16 v[64:79], v[124:127], v[140:143], v[64:79]
	ds_read_b64_tr_b16 v[140:141], v227 offset:0x3200
	ds_read_b64_tr_b16 v[142:143], v227 offset:0x3a00
	s_waitcnt lgkmcnt(0)
	v_mfma_f32_32x32x16_bf16 v[48:63], v[80:83], v[128:131], v[48:63]
	ds_read_b64_tr_b16 v[128:129], v227 offset:0x400
	ds_read_b64_tr_b16 v[130:131], v227 offset:0xc00
	v_mfma_f32_32x32x16_bf16 v[48:63], v[116:119], v[132:135], v[48:63]
	ds_read_b64_tr_b16 v[132:133], v227 offset:0x1400
	ds_read_b64_tr_b16 v[134:135], v227 offset:0x1c00
	v_mfma_f32_32x32x16_bf16 v[48:63], v[120:123], v[136:139], v[48:63]
	ds_read_b64_tr_b16 v[136:137], v227 offset:0x2400
	ds_read_b64_tr_b16 v[138:139], v227 offset:0x2c00
	v_mfma_f32_32x32x16_bf16 v[48:63], v[124:127], v[140:143], v[48:63]
	ds_read_b64_tr_b16 v[140:141], v227 offset:0x3400
	ds_read_b64_tr_b16 v[142:143], v227 offset:0x3c00
	s_waitcnt lgkmcnt(0)
	v_mfma_f32_32x32x16_bf16 v[32:47], v[80:83], v[128:131], v[32:47]
	ds_read_b64_tr_b16 v[128:129], v227 offset:0x600
	ds_read_b64_tr_b16 v[130:131], v227 offset:0xe00
	v_mfma_f32_32x32x16_bf16 v[32:47], v[116:119], v[132:135], v[32:47]
	ds_read_b64_tr_b16 v[132:133], v227 offset:0x1600
	ds_read_b64_tr_b16 v[134:135], v227 offset:0x1e00
	v_mfma_f32_32x32x16_bf16 v[32:47], v[120:123], v[136:139], v[32:47]
	ds_read_b64_tr_b16 v[136:137], v227 offset:0x2600
	ds_read_b64_tr_b16 v[138:139], v227 offset:0x2e00
	v_mfma_f32_32x32x16_bf16 v[32:47], v[124:127], v[140:143], v[32:47]
	ds_read_b64_tr_b16 v[140:141], v227 offset:0x3600
	ds_read_b64_tr_b16 v[142:143], v227 offset:0x3e00
	s_waitcnt lgkmcnt(0)
	s_barrier
	s_waitcnt vmcnt(0)
	ds_write_b128 v237, v[2:5]
	ds_write_b128 v238, v[6:9]
	ds_write_b32 v242, v246
	ds_write_b128 v222, v[10:13] offset:32768
	ds_write_b128 v222, v[210:213] offset:40960
	v_mfma_f32_32x32x16_bf16 v[16:31], v[80:83], v[128:131], v[16:31]
	s_cmp_le_i32 s68, s57
	s_cselect_b64 s[28:29], -1, 0
	s_cmp_gt_i32 s4, s58
	s_cselect_b64 s[4:5], -1, 0
	s_and_b64 s[4:5], s[28:29], s[4:5]
	s_and_b64 vcc, exec, s[4:5]
	v_mfma_f32_32x32x16_bf16 v[16:31], v[116:119], v[132:135], v[16:31]
	v_mfma_f32_32x32x16_bf16 v[16:31], v[120:123], v[136:139], v[16:31]
	v_mfma_f32_32x32x16_bf16 v[16:31], v[124:127], v[140:143], v[16:31]
	s_cbranch_vccnz .LBB0_1249
	v_add_u32_e32 v0, 0x107b, v243
	v_cmp_gt_u32_e32 vcc, s81, v0
	v_add_u32_e32 v0, 0x5b, v243
	s_nop 0
	v_cndmask_b32_e32 v100, v216, v100, vcc
	v_cmp_lt_u32_e32 vcc, s82, v0
	v_add_u32_e32 v0, 0x7a, v243
	s_nop 0
	v_cndmask_b32_e32 v84, v216, v84, vcc
	v_cmp_lt_u32_e32 vcc, s82, v0
	v_add_u32_e32 v0, 0x5a, v243
	s_nop 0
	v_cndmask_b32_e32 v101, v216, v101, vcc
	v_cmp_lt_u32_e32 vcc, s82, v0
	v_add_u32_e32 v0, 0x79, v243
	s_nop 0
	v_cndmask_b32_e32 v85, v216, v85, vcc
	v_cmp_lt_u32_e32 vcc, s82, v0
	v_add_u32_e32 v0, 0x59, v243
	s_nop 0
	v_cndmask_b32_e32 v102, v216, v102, vcc
	v_cmp_lt_u32_e32 vcc, s82, v0
	v_add_u32_e32 v0, 0x78, v243
	s_nop 0
	v_cndmask_b32_e32 v86, v216, v86, vcc
	v_cmp_lt_u32_e32 vcc, s82, v0
	v_add_u32_e32 v0, 0x58, v243
	s_nop 0
	v_cndmask_b32_e32 v103, v216, v103, vcc
	v_cmp_lt_u32_e32 vcc, s82, v0
	v_add_u32_e32 v0, 0x73, v243
	s_nop 0
	v_cndmask_b32_e32 v87, v216, v87, vcc
	v_cmp_lt_u32_e32 vcc, s82, v0
	v_add_u32_e32 v0, 0x53, v243
	s_nop 0
	v_cndmask_b32_e32 v104, v216, v104, vcc
	v_cmp_lt_u32_e32 vcc, s82, v0
	v_add_u32_e32 v0, 0x72, v243
	s_nop 0
	v_cndmask_b32_e32 v88, v216, v88, vcc
	v_cmp_lt_u32_e32 vcc, s82, v0
	v_add_u32_e32 v0, 0x52, v243
	s_nop 0
	v_cndmask_b32_e32 v105, v216, v105, vcc
	v_cmp_lt_u32_e32 vcc, s82, v0
	v_add_u32_e32 v0, 0x71, v243
	s_nop 0
	v_cndmask_b32_e32 v89, v216, v89, vcc
	v_cmp_lt_u32_e32 vcc, s82, v0
	v_add_u32_e32 v0, 0x51, v243
	s_nop 0
	v_cndmask_b32_e32 v106, v216, v106, vcc
	v_cmp_lt_u32_e32 vcc, s82, v0
	v_add_u32_e32 v0, 0x70, v243
	s_nop 0
	v_cndmask_b32_e32 v90, v216, v90, vcc
	v_cmp_lt_u32_e32 vcc, s82, v0
	v_add_u32_e32 v0, 0x50, v243
	s_nop 0
	v_cndmask_b32_e32 v107, v216, v107, vcc
	v_cmp_lt_u32_e32 vcc, s82, v0
	v_add_u32_e32 v0, 0x6b, v243
	s_nop 0
	v_cndmask_b32_e32 v91, v216, v91, vcc
	v_cmp_lt_u32_e32 vcc, s82, v0
	v_add_u32_e32 v0, 0x4b, v243
	s_nop 0
	v_cndmask_b32_e32 v108, v216, v108, vcc
	v_cmp_lt_u32_e32 vcc, s82, v0
	v_add_u32_e32 v0, 0x6a, v243
	s_nop 0
	v_cndmask_b32_e32 v92, v216, v92, vcc
	v_cmp_lt_u32_e32 vcc, s82, v0
	v_add_u32_e32 v0, 0x4a, v243
	s_nop 0
	v_cndmask_b32_e32 v109, v216, v109, vcc
	v_cmp_lt_u32_e32 vcc, s82, v0
	v_add_u32_e32 v0, 0x69, v243
	s_nop 0
	v_cndmask_b32_e32 v93, v216, v93, vcc
	v_cmp_lt_u32_e32 vcc, s82, v0
	v_add_u32_e32 v0, 0x49, v243
	s_nop 0
	v_cndmask_b32_e32 v110, v216, v110, vcc
	v_cmp_lt_u32_e32 vcc, s82, v0
	v_add_u32_e32 v0, 0x68, v243
	s_nop 0
	v_cndmask_b32_e32 v94, v216, v94, vcc
	v_cmp_lt_u32_e32 vcc, s82, v0
	v_add_u32_e32 v0, 0x48, v243
	s_nop 0
	v_cndmask_b32_e32 v111, v216, v111, vcc
	v_cmp_lt_u32_e32 vcc, s82, v0
	v_add_u32_e32 v0, 0x63, v243
	s_nop 0
	v_cndmask_b32_e32 v95, v216, v95, vcc
	v_cmp_lt_u32_e32 vcc, s82, v0
	v_add_u32_e32 v0, 0x43, v243
	s_nop 0
	v_cndmask_b32_e32 v112, v216, v112, vcc
	v_cmp_lt_u32_e32 vcc, s82, v0
	v_add_u32_e32 v0, 0x62, v243
	s_nop 0
	v_cndmask_b32_e32 v96, v216, v96, vcc
	v_cmp_lt_u32_e32 vcc, s82, v0
	v_add_u32_e32 v0, 0x42, v243
	s_nop 0
	v_cndmask_b32_e32 v113, v216, v113, vcc
	v_cmp_lt_u32_e32 vcc, s82, v0
	v_add_u32_e32 v0, 0x61, v243
	s_nop 0
	v_cndmask_b32_e32 v97, v216, v97, vcc
	v_cmp_lt_u32_e32 vcc, s82, v0
	v_add_u32_e32 v0, 0x41, v243
	s_nop 0
	v_cndmask_b32_e32 v114, v216, v114, vcc
	v_cmp_lt_u32_e32 vcc, s82, v0
	v_add_u32_e32 v0, 0x60, v243
	s_nop 0
	v_cndmask_b32_e32 v98, v216, v98, vcc
	v_cmp_lt_u32_e32 vcc, s82, v0
	v_add_u32_e32 v0, 64, v243
	s_nop 0
	v_cndmask_b32_e32 v115, v216, v115, vcc
	v_cmp_lt_u32_e32 vcc, s82, v0
	s_nop 1
	v_cndmask_b32_e32 v99, v216, v99, vcc
; __device__ __forceinline__ void partialSM(f32x16& p0, f32x16& p1, float& m_reg, float& mn, float& alpha) {
;     float pmax = p0[0]; for (int r = 1; r < 16; ++r) pmax = fmaxf(pmax, p0[r]); for (int r = 0; r < 16; ++r) pmax = fmaxf(pmax, p1[r]);
;     { auto rr = __builtin_amdgcn_permlane32_swap(__float_as_uint(pmax), __float_as_uint(pmax), false, false);
;       pmax = fmaxf(__uint_as_float(rr[0]), __uint_as_float(rr[1])); }
;     constexpr float C2 = 1.4426950408889634f * SCALE;
;     if (__builtin_expect(__all((pmax - m_reg) * SCALE <= THR), 1)) { mn = m_reg; alpha = 1.f; }
;     else { mn = fmaxf(m_reg, pmax); alpha = __builtin_amdgcn_exp2f((m_reg - mn) * C2); m_reg = mn; }
.LBB0_1249:
	v_max_f32_e32 v0, v101, v101
	v_max_f32_e32 v15, v100, v100
	v_max_f32_e32 v0, v15, v0
	v_max3_f32 v0, v0, v102, v103
	v_max3_f32 v0, v0, v104, v105
	v_max3_f32 v0, v0, v106, v107
	v_max3_f32 v0, v0, v108, v109
	v_max3_f32 v0, v0, v110, v111
	v_max3_f32 v0, v0, v112, v113
	v_max3_f32 v0, v0, v114, v115
	v_max3_f32 v0, v0, v84, v85
	v_max3_f32 v0, v0, v86, v87
	v_max3_f32 v0, v0, v88, v89
	v_max3_f32 v0, v0, v90, v91
	v_max3_f32 v0, v0, v92, v93
	v_max3_f32 v0, v0, v94, v95
	v_max3_f32 v0, v0, v96, v97
	v_max3_f32 v0, v0, v98, v99
	v_mov_b32_e32 v15, v0
	s_nop 1
	v_permlane32_swap_b32_e32 v0, v15
	v_max_f32_e32 v15, v15, v15
	v_max_f32_e32 v0, v0, v0
	v_max_f32_e32 v0, v0, v15
	v_sub_f32_e32 v15, v0, v180
	v_mul_f32_e32 v15, 0x3db504f3, v15
	v_cmp_ge_f32_e32 vcc, s83, v15
	v_max_f32_e32 v15, v180, v180
	v_max_f32_e32 v0, v15, v0
	v_sub_f32_e32 v15, v180, v0
	v_mul_f32_e32 v15, 0x3e0293ee, v15
	v_exp_f32_e32 v15, v15
	s_cmp_eq_u64 vcc, exec
	s_cselect_b64 s[4:5], -1, 0
	v_cndmask_b32_e64 v15, v15, 1.0, s[4:5]
	v_cmp_gt_f32_e32 vcc, 1.0, v15
	s_cbranch_vccz .LBB0_1253
	s_and_saveexec_b64 s[28:29], s[2:3]
	ds_write_b32 v226, v15 offset:128
	s_or_b64 exec, exec, s[28:29]
	s_waitcnt lgkmcnt(0)
	ds_read_b128 v[80:83], v225 offset:224
	ds_read_b128 v[116:119], v225 offset:192
	ds_read_b128 v[120:123], v225 offset:160
	ds_read_b128 v[124:127], v225 offset:128
	s_waitcnt lgkmcnt(3)
	v_pk_mul_f32 v[78:79], v[78:79], v[82:83]
	s_waitcnt lgkmcnt(2)
	v_pk_mul_f32 v[74:75], v[74:75], v[118:119]
	s_waitcnt lgkmcnt(1)
	v_pk_mul_f32 v[70:71], v[70:71], v[122:123]
	s_waitcnt lgkmcnt(0)
	v_pk_mul_f32 v[66:67], v[66:67], v[126:127]
	v_pk_mul_f32 v[76:77], v[76:77], v[80:81]
	v_pk_mul_f32 v[72:73], v[72:73], v[116:117]
	v_pk_mul_f32 v[68:69], v[68:69], v[120:121]
	v_pk_mul_f32 v[64:65], v[64:65], v[124:125]
	v_pk_mul_f32 v[62:63], v[62:63], v[82:83]
	v_pk_mul_f32 v[58:59], v[58:59], v[118:119]
	v_pk_mul_f32 v[54:55], v[54:55], v[122:123]
	v_pk_mul_f32 v[50:51], v[50:51], v[126:127]
	v_pk_mul_f32 v[60:61], v[60:61], v[80:81]
	v_pk_mul_f32 v[56:57], v[56:57], v[116:117]
	v_pk_mul_f32 v[52:53], v[52:53], v[120:121]
	v_pk_mul_f32 v[48:49], v[48:49], v[124:125]
	v_pk_mul_f32 v[46:47], v[46:47], v[82:83]
	v_pk_mul_f32 v[42:43], v[42:43], v[118:119]
	v_pk_mul_f32 v[38:39], v[38:39], v[122:123]
	v_pk_mul_f32 v[34:35], v[34:35], v[126:127]
	v_pk_mul_f32 v[44:45], v[44:45], v[80:81]
	v_pk_mul_f32 v[40:41], v[40:41], v[116:117]
	v_pk_mul_f32 v[36:37], v[36:37], v[120:121]
	v_pk_mul_f32 v[32:33], v[32:33], v[124:125]
	v_pk_mul_f32 v[30:31], v[30:31], v[82:83]
	v_pk_mul_f32 v[26:27], v[26:27], v[118:119]
	v_pk_mul_f32 v[22:23], v[22:23], v[122:123]
	v_pk_mul_f32 v[18:19], v[18:19], v[126:127]
	v_pk_mul_f32 v[28:29], v[28:29], v[80:81]
	v_pk_mul_f32 v[24:25], v[24:25], v[116:117]
	v_pk_mul_f32 v[20:21], v[20:21], v[120:121]
	v_pk_mul_f32 v[16:17], v[16:17], v[124:125]

; template <int VB, bool SK>
; __device__ __forceinline__ void pv_tile(f32x16* o, int vb0, bf16x8 pa0, bf16x8 pa1, bf16x8 pa2, bf16x8 pa3, bool act) {
;     ...
;     PV_D0(0); PV_D0(1); PV_D0(2); PV_D0(3);
.LBB0_1255:
	ds_read_b64_tr_b16 v[202:203], v227 offset:0x4000
	ds_read_b64_tr_b16 v[204:205], v227 offset:0x4800
	ds_read_b64_tr_b16 v[196:197], v227 offset:0x5000
	ds_read_b64_tr_b16 v[198:199], v227 offset:0x5800
	ds_read_b64_tr_b16 v[210:211], v227 offset:0x6000
	ds_read_b64_tr_b16 v[212:213], v227 offset:0x6800
	ds_read_b64_tr_b16 v[206:207], v227 offset:0x7000
	ds_read_b64_tr_b16 v[208:209], v227 offset:0x7800
	s_waitcnt lgkmcnt(0)
	s_add_i32 s4, s68, 64
	s_add_i32 s69, s68, 1
	v_mfma_f32_32x32x16_bf16 v[64:79], v[180:183], v[202:205], v[64:79]
	v_mfma_f32_32x32x16_bf16 v[64:79], v[184:187], v[196:199], v[64:79]
	ds_read_b64_tr_b16 v[196:197], v227 offset:0x4200
	ds_read_b64_tr_b16 v[198:199], v227 offset:0x4a00
	ds_read_b64_tr_b16 v[202:203], v227 offset:0x5200
	ds_read_b64_tr_b16 v[204:205], v227 offset:0x5a00
	v_mfma_f32_32x32x16_bf16 v[64:79], v[188:191], v[210:213], v[64:79]
	v_mfma_f32_32x32x16_bf16 v[64:79], v[192:195], v[206:209], v[64:79]
	ds_read_b64_tr_b16 v[206:207], v227 offset:0x6200
	ds_read_b64_tr_b16 v[208:209], v227 offset:0x6a00
	ds_read_b64_tr_b16 v[210:211], v227 offset:0x7200
	ds_read_b64_tr_b16 v[212:213], v227 offset:0x7a00
	s_waitcnt lgkmcnt(0)
	v_mfma_f32_32x32x16_bf16 v[48:63], v[180:183], v[196:199], v[48:63]
	ds_read_b64_tr_b16 v[196:197], v227 offset:0x4400
	ds_read_b64_tr_b16 v[198:199], v227 offset:0x4c00
	v_mfma_f32_32x32x16_bf16 v[48:63], v[184:187], v[202:205], v[48:63]
	ds_read_b64_tr_b16 v[202:203], v227 offset:0x5400
	ds_read_b64_tr_b16 v[204:205], v227 offset:0x5c00
	v_mfma_f32_32x32x16_bf16 v[48:63], v[188:191], v[206:209], v[48:63]
	ds_read_b64_tr_b16 v[206:207], v227 offset:0x6400
	ds_read_b64_tr_b16 v[208:209], v227 offset:0x6c00
	v_mfma_f32_32x32x16_bf16 v[48:63], v[192:195], v[210:213], v[48:63]
	ds_read_b64_tr_b16 v[210:211], v227 offset:0x7400
	ds_read_b64_tr_b16 v[212:213], v227 offset:0x7c00
	s_waitcnt lgkmcnt(0)
	v_mfma_f32_32x32x16_bf16 v[32:47], v[180:183], v[196:199], v[32:47]
	ds_read_b64_tr_b16 v[196:197], v227 offset:0x4600
	ds_read_b64_tr_b16 v[198:199], v227 offset:0x4e00
	v_mfma_f32_32x32x16_bf16 v[32:47], v[184:187], v[202:205], v[32:47]
	ds_read_b64_tr_b16 v[202:203], v227 offset:0x5600
	ds_read_b64_tr_b16 v[204:205], v227 offset:0x5e00
	v_mfma_f32_32x32x16_bf16 v[32:47], v[188:191], v[206:209], v[32:47]
	ds_read_b64_tr_b16 v[206:207], v227 offset:0x6600
	ds_read_b64_tr_b16 v[208:209], v227 offset:0x6e00
	v_mfma_f32_32x32x16_bf16 v[32:47], v[192:195], v[210:213], v[32:47]
	ds_read_b64_tr_b16 v[210:211], v227 offset:0x7600
	ds_read_b64_tr_b16 v[212:213], v227 offset:0x7e00
	s_waitcnt lgkmcnt(0)
	s_barrier
	s_andn2_b64 vcc, exec, s[28:29]
	s_cbranch_vccnz .Lattn_h2_nowrite
	s_waitcnt vmcnt(0)
	ds_write_b128 v237, v[2:5] offset:16384
	ds_write_b128 v238, v[6:9] offset:16384
	ds_write_b32 v242, v246 offset:256
	ds_write_b128 v222, v[10:13] offset:49152
	ds_write_b128 v222, v[176:179] offset:57344
; __device__ __forceinline__ void mask_tile(f32x16& p0, f32x16& p1, int dq, unsigned W) {
;     const float NEG = -__builtin_inff();
; #pragma unroll
;     for (int r = 0; r < 16; ++r) {
;         const int c = (r & 3) + 8 * (r >> 2);
;         if ((unsigned)(dq - c) >= W) p0[r] = NEG;
;         if ((unsigned)(dq - c - 32) >= W) p1[r] = NEG;
;     }
; }
; __device__ __forceinline__ void partialSM(f32x16& p0, f32x16& p1, float& m_reg, float& mn, float& alpha) {
;     float pmax = p0[0]; for (int r = 1; r < 16; ++r) pmax = fmaxf(pmax, p0[r]); for (int r = 0; r < 16; ++r) pmax = fmaxf(pmax, p1[r]);
;     { auto rr = __builtin_amdgcn_permlane32_swap(__float_as_uint(pmax), __float_as_uint(pmax), false, false);
;       pmax = fmaxf(__uint_as_float(rr[0]), __uint_as_float(rr[1])); }
;     constexpr float C2 = 1.4426950408889634f * SCALE;
;     if (__builtin_expect(__all((pmax - m_reg) * SCALE <= THR), 1)) { mn = m_reg; alpha = 1.f; }
;     else { mn = fmaxf(m_reg, pmax); alpha = __builtin_amdgcn_exp2f((m_reg - mn) * C2); m_reg = mn; }
.Lattn_h2_nowrite:
	v_mfma_f32_32x32x16_bf16 v[16:31], v[180:183], v[196:199], v[16:31]
	s_cmp_le_i32 s4, s57
	s_cselect_b64 s[4:5], -1, 0
	s_cmp_gt_i32 s69, s58
	s_cselect_b64 s[72:73], -1, 0
	s_and_b64 s[4:5], s[4:5], s[72:73]
	s_and_b64 vcc, exec, s[4:5]
	v_mfma_f32_32x32x16_bf16 v[16:31], v[184:187], v[202:205], v[16:31]
	v_mfma_f32_32x32x16_bf16 v[16:31], v[188:191], v[206:209], v[16:31]
	v_mfma_f32_32x32x16_bf16 v[16:31], v[192:195], v[210:213], v[16:31]
	s_cbranch_vccnz .LBB0_1257
	v_add_u32_e32 v0, 0x103b, v243
	v_cmp_gt_u32_e32 vcc, s81, v0
	v_add_u32_e32 v0, 27, v243
	s_nop 0
	v_cndmask_b32_e32 v128, v216, v128, vcc
	v_cmp_lt_u32_e32 vcc, s82, v0
	v_add_u32_e32 v0, 58, v243
	s_nop 0
	v_cndmask_b32_e32 v112, v216, v112, vcc
	v_cmp_lt_u32_e32 vcc, s82, v0
	v_add_u32_e32 v0, 26, v243
	s_nop 0
	v_cndmask_b32_e32 v129, v216, v129, vcc
	v_cmp_lt_u32_e32 vcc, s82, v0
	v_add_u32_e32 v0, 57, v243
	s_nop 0
	v_cndmask_b32_e32 v113, v216, v113, vcc
	v_cmp_lt_u32_e32 vcc, s82, v0
	v_add_u32_e32 v0, 25, v243
	s_nop 0
	v_cndmask_b32_e32 v130, v216, v130, vcc
	v_cmp_lt_u32_e32 vcc, s82, v0
	v_add_u32_e32 v0, 56, v243
	s_nop 0
	v_cndmask_b32_e32 v114, v216, v114, vcc
	v_cmp_lt_u32_e32 vcc, s82, v0
	v_add_u32_e32 v0, 24, v243
	s_nop 0
	v_cndmask_b32_e32 v131, v216, v131, vcc
	v_cmp_lt_u32_e32 vcc, s82, v0
	v_add_u32_e32 v0, 51, v243
	s_nop 0
	v_cndmask_b32_e32 v115, v216, v115, vcc
	v_cmp_lt_u32_e32 vcc, s82, v0
	v_add_u32_e32 v0, 19, v243
	s_nop 0
	v_cndmask_b32_e32 v132, v216, v132, vcc
	v_cmp_lt_u32_e32 vcc, s82, v0
	v_add_u32_e32 v0, 50, v243
	s_nop 0
	v_cndmask_b32_e32 v116, v216, v116, vcc
	v_cmp_lt_u32_e32 vcc, s82, v0
	v_add_u32_e32 v0, 18, v243
	s_nop 0
	v_cndmask_b32_e32 v133, v216, v133, vcc
	v_cmp_lt_u32_e32 vcc, s82, v0
	v_add_u32_e32 v0, 49, v243
	s_nop 0
	v_cndmask_b32_e32 v117, v216, v117, vcc
	v_cmp_lt_u32_e32 vcc, s82, v0
	v_add_u32_e32 v0, 17, v243
	s_nop 0
	v_cndmask_b32_e32 v134, v216, v134, vcc
	v_cmp_lt_u32_e32 vcc, s82, v0
	v_add_u32_e32 v0, 48, v243
	s_nop 0
	v_cndmask_b32_e32 v118, v216, v118, vcc
	v_cmp_lt_u32_e32 vcc, s82, v0
	v_add_u32_e32 v0, 16, v243
	s_nop 0
	v_cndmask_b32_e32 v135, v216, v135, vcc
	v_cmp_lt_u32_e32 vcc, s82, v0
	v_add_u32_e32 v0, 43, v243
	s_nop 0
	v_cndmask_b32_e32 v119, v216, v119, vcc
	v_cmp_lt_u32_e32 vcc, s82, v0
	v_add_u32_e32 v0, 11, v243
	s_nop 0
	v_cndmask_b32_e32 v136, v216, v136, vcc
	v_cmp_lt_u32_e32 vcc, s82, v0
	v_add_u32_e32 v0, 42, v243
	s_nop 0
	v_cndmask_b32_e32 v120, v216, v120, vcc
	v_cmp_lt_u32_e32 vcc, s82, v0
	v_add_u32_e32 v0, 10, v243
	s_nop 0
	v_cndmask_b32_e32 v137, v216, v137, vcc
	v_cmp_lt_u32_e32 vcc, s82, v0
	v_add_u32_e32 v0, 41, v243
	s_nop 0
	v_cndmask_b32_e32 v121, v216, v121, vcc
	v_cmp_lt_u32_e32 vcc, s82, v0
	v_add_u32_e32 v0, 9, v243
	s_nop 0
	v_cndmask_b32_e32 v138, v216, v138, vcc
	v_cmp_lt_u32_e32 vcc, s82, v0
	v_add_u32_e32 v0, 40, v243
	s_nop 0
	v_cndmask_b32_e32 v122, v216, v122, vcc
	v_cmp_lt_u32_e32 vcc, s82, v0
	v_add_u32_e32 v0, 8, v243
	s_nop 0
	v_cndmask_b32_e32 v139, v216, v139, vcc
	v_cmp_lt_u32_e32 vcc, s82, v0
	v_add_u32_e32 v0, 35, v243
	s_nop 0
	v_cndmask_b32_e32 v123, v216, v123, vcc
	v_cmp_lt_u32_e32 vcc, s82, v0
	v_add_u32_e32 v0, 3, v243
	s_nop 0
	v_cndmask_b32_e32 v140, v216, v140, vcc
	v_cmp_lt_u32_e32 vcc, s82, v0
	v_add_u32_e32 v0, 34, v243
	s_nop 0
	v_cndmask_b32_e32 v124, v216, v124, vcc
	v_cmp_lt_u32_e32 vcc, s82, v0
	v_add_u32_e32 v0, 2, v243
	s_nop 0
	v_cndmask_b32_e32 v141, v216, v141, vcc
	v_cmp_lt_u32_e32 vcc, s82, v0
	v_add_u32_e32 v0, 33, v243
	s_nop 0
	v_cndmask_b32_e32 v125, v216, v125, vcc
	v_cmp_lt_u32_e32 vcc, s82, v0
	v_add_u32_e32 v0, 1, v243
	s_nop 0
	v_cndmask_b32_e32 v142, v216, v142, vcc
	v_cmp_lt_u32_e32 vcc, s82, v0
	v_add_u32_e32 v0, 32, v243
	s_nop 0
	v_cndmask_b32_e32 v126, v216, v126, vcc
	v_cmp_lt_u32_e32 vcc, s82, v0
	s_nop 1
	v_cndmask_b32_e32 v143, v216, v143, vcc
	v_cmp_lt_u32_e32 vcc, s82, v243
	s_nop 1
	v_cndmask_b32_e32 v127, v216, v127, vcc
.LBB0_1257:
	v_max_f32_e32 v0, v129, v129
	v_max_f32_e32 v180, v128, v128
	v_max_f32_e32 v0, v180, v0
	v_max3_f32 v0, v0, v130, v131
	v_max3_f32 v0, v0, v132, v133
	v_max3_f32 v0, v0, v134, v135
	v_max3_f32 v0, v0, v136, v137
	v_max3_f32 v0, v0, v138, v139
	v_max3_f32 v0, v0, v140, v141
	v_max3_f32 v0, v0, v142, v143
	v_max3_f32 v0, v0, v112, v113
	v_max3_f32 v0, v0, v114, v115
	v_max3_f32 v0, v0, v116, v117
	v_max3_f32 v0, v0, v118, v119
	v_max3_f32 v0, v0, v120, v121
	v_max3_f32 v0, v0, v122, v123
	v_max3_f32 v0, v0, v124, v125
	v_max3_f32 v0, v0, v126, v127
	v_mov_b32_e32 v180, v0
	s_nop 1
	v_permlane32_swap_b32_e32 v0, v180
	v_max_f32_e32 v180, v180, v180
	v_max_f32_e32 v0, v0, v0
	v_max_f32_e32 v0, v0, v180
	v_sub_f32_e32 v180, v0, v247
	v_mul_f32_e32 v180, 0x3db504f3, v180
	v_cmp_ge_f32_e32 vcc, s83, v180
	s_cmp_eq_u64 vcc, exec
	s_cselect_b64 s[4:5], -1, 0
.LBB0_1259:
	s_waitcnt vmcnt(3)
	v_max_f32_e32 v2, v247, v247
	v_max_f32_e32 v2, v2, v0
	v_sub_f32_e32 v0, v247, v2
	v_mul_f32_e32 v0, 0x3e0293ee, v0
	v_exp_f32_e32 v0, v0
	s_nop 0
	v_cndmask_b32_e64 v0, v0, 1.0, s[4:5]
	v_cmp_gt_f32_e32 vcc, 1.0, v0
	s_cbranch_vccz .LBB0_1246
	s_and_saveexec_b64 s[28:29], s[2:3]
	s_cbranch_execz .LBB0_1245
	ds_write_b32 v226, v0 offset:128
	s_branch .LBB0_1245
